# P8a: blocks owning a sample item skip their 8th prompt item; other blocks take it as a 9th (balances sample vs prompt item cost)
# baseline (speedup 1.0000x reference)
.LBB0_1645:
	s_or_b64 exec, exec, s[8:9]
	s_add_i32 s0, s18, 3
	s_ashr_i32 s1, s0, 31
	v_lshl_add_u64 v[4:5], v[4:5], 1, s[12:13]
	s_lshl_b64 s[0:1], s[0:1], 12
	s_add_i32 s2, s2, s92
	s_add_i32 s18, s18, s24
	v_cvt_pk_bf16_f32 v0, v0, v1
	v_cvt_pk_bf16_f32 v1, v2, v3
	v_lshl_add_u64 v[2:3], v[4:5], 0, s[0:1]
	s_cmpk_eq_u32 s92, 0x100
	s_cbranch_scc0 .Lp8a_lat
	s_and_b32 s98, s2, 0xff
	s_cmpk_lt_u32 s98, 0x80
	s_cbranch_scc0 .Lp8a_dealB
	s_sub_i32 s98, s2, 0x700
	s_cmpk_lt_u32 s98, 0x80
	s_cbranch_scc0 .Lp8a_lat
	s_addk_i32 s2, 0x100
	s_addk_i32 s18, 0x400
	s_branch .Lp8a_lat
.Lp8a_dealB:
	s_sub_i32 s98, s2, 0x800
	s_cmpk_lt_u32 s98, 0x80
	s_cbranch_scc0 .Lp8a_dealB2
	s_movk_i32 s2, 0x1000
	s_branch .Lp8a_lat
.Lp8a_dealB2:
	s_cmpk_lt_u32 s98, 0x100
	s_cbranch_scc0 .Lp8a_lat
	s_addk_i32 s2, 0xfe80
	s_addk_i32 s18, 0xfa00
.Lp8a_lat:
	s_cmpk_gt_i32 s2, 0x87f
	global_store_dwordx2 v[2:3], v[0:1], off
	s_cbranch_scc1 .LBB0_1974
